# WY chain loop hand-scheduled (single LDS burst, interleaved halves, early flag poll) + wy_issue waits removed + attention QK 4-deep LDS prefetch ring
# speedup vs baseline: 1.0269x; 1.0269x over previous
; #define LAS __attribute__((address_space(3)))
; __device__ __forceinline__ void rw_wy(const Args& a, LAS unsigned char* lds, int bh, int tid) {
;     ...
;     } else {
;         float* YB = (float*)(a.ws + WS_YB);
;         const int vl = lane & 15, g = lane >> 4;
;         const f32x4 zero4 = {0.f, 0.f, 0.f, 0.f};
;         for (int c = 1; c < WY_NCH; ++c) { const int p = c % WY_NP; const LAS unsigned char* slot = lds + p * WY_SLOT;
;             while (__hip_atomic_load(flags + p, __ATOMIC_ACQUIRE, __HIP_MEMORY_SCOPE_WORKGROUP) != c + 1) __builtin_amdgcn_s_sleep(1);
;             const int fo = vl * 64 + g * 16;
;             f32x4 PT4[4];
; #pragma unroll
;             for (int n = 0; n < 4; ++n) PT4[n] = *(const LAS f32x4*)(slot + WY_PT + (16 * n + 4 * g) * 4);
;             const bf16x8 az0 = *(const LAS bf16x8*)(slot + WY_AZ + fo), az1 = *(const LAS bf16x8*)(slot + WY_AZ + 1024 + fo), ay0 = *(const LAS bf16x8*)(slot + WY_AY1 + fo), ay1 = *(const LAS bf16x8*)(slot + WY_AY1 + 1024 + fo);
;             const bf16x8 au = *(const LAS bf16x8*)(slot + WY_AU + fo), ay2 = *(const LAS bf16x8*)(slot + WY_AY2 + fo);
;             const size_t tokg = (size_t)b * SEQ + (size_t)c * WY_T + 4 * g;
.LBB0_1408:
	s_cmp_lt_i32 s5, 2
	s_mov_b64 s[0:1], -1
	s_waitcnt lgkmcnt(0)
	s_barrier
	s_cbranch_scc0 .LBB0_1416
	s_ashr_i32 s93, s92, 31
	s_lshl_b64 s[0:1], s[92:93], 13
	v_or_b32_e32 v92, s0, v120
	s_lshl_b32 s0, s4, 8
	s_add_u32 s0, s50, s0
	v_mov_b32_e32 v93, s1
	s_addc_u32 s1, s51, 0
	s_lshl_b32 s2, s5, 2
	v_ashrrev_i32_e32 v163, 31, v162
	s_add_i32 s2, s2, 0
	v_lshlrev_b32_e32 v104, 5, v162
	v_lshl_add_u64 v[94:95], v[162:163], 2, s[0:1]
	s_add_i32 s2, s2, 0x19e20
	v_or_b32_e32 v105, 0x200, v104
	v_lshl_add_u64 v[96:97], v[94:95], 0, 64
	s_mov_b32 s0, 1
	s_waitcnt vmcnt(0)
	v_mov_b32_e32 v195, 0
	s_branch .LBB0_1411

; #define LAS __attribute__((address_space(3)))
; __device__ __forceinline__ void rw_wy(const Args& a, LAS unsigned char* lds, int bh, int tid) {
;     ...
;         for (int c = 1; c < WY_NCH; ++c) { const int p = c % WY_NP; const LAS unsigned char* slot = lds + p * WY_SLOT;
;             while (__hip_atomic_load(flags + p, __ATOMIC_ACQUIRE, __HIP_MEMORY_SCOPE_WORKGROUP) != c + 1) __builtin_amdgcn_s_sleep(1);
.LBB0_1411:
	s_mul_i32 s1, s0, 0xaaab
	s_lshr_b32 s1, s1, 18
	s_mul_i32 s1, s1, 6
	s_sub_i32 s1, s0, s1
	s_and_b32 s1, s1, 0xffff
	s_lshl_b32 s3, s1, 2
	s_add_i32 s28, s3, 0
	s_add_i32 s28, s28, 0x19e00
	s_add_i32 s3, s0, 1
	v_cmp_eq_u32_e32 vcc, s3, v195
	s_cbranch_vccnz .LBB0_1413
	v_mov_b32_e32 v32, s28
	ds_read_b32 v32, v32
	s_waitcnt lgkmcnt(0)
	v_cmp_eq_u32_e32 vcc, s3, v32
	s_cbranch_vccnz .LBB0_1413

; #define LAS __attribute__((address_space(3)))
; __device__ __forceinline__ void rw_wy(const Args& a, LAS unsigned char* lds, int bh, int tid) {
;     ...
;         for (int c = 1; c < WY_NCH; ++c) { const int p = c % WY_NP; const LAS unsigned char* slot = lds + p * WY_SLOT;
;             while (__hip_atomic_load(flags + p, __ATOMIC_ACQUIRE, __HIP_MEMORY_SCOPE_WORKGROUP) != c + 1) __builtin_amdgcn_s_sleep(1);
;             const int fo = vl * 64 + g * 16;
;             f32x4 PT4[4];
; #pragma unroll
;             for (int n = 0; n < 4; ++n) PT4[n] = *(const LAS f32x4*)(slot + WY_PT + (16 * n + 4 * g) * 4);
;             const bf16x8 az0 = *(const LAS bf16x8*)(slot + WY_AZ + fo), az1 = *(const LAS bf16x8*)(slot + WY_AZ + 1024 + fo), ay0 = *(const LAS bf16x8*)(slot + WY_AY1 + fo), ay1 = *(const LAS bf16x8*)(slot + WY_AY1 + 1024 + fo);
;             const bf16x8 au = *(const LAS bf16x8*)(slot + WY_AU + fo), ay2 = *(const LAS bf16x8*)(slot + WY_AY2 + fo);
;             const size_t tokg = (size_t)b * SEQ + (size_t)c * WY_T + 4 * g;
; #pragma unroll
;             for (int vt = 0; vt < 2; ++vt) { const int v = 32 * wave + 16 * vt + vl;
;                 u32x4 s0w, s1w; s0w.x = pk2(ST[vt][0].x, ST[vt][0].y); s0w.y = pk2(ST[vt][0].z, ST[vt][0].w); s0w.z = pk2(ST[vt][1].x, ST[vt][1].y); s0w.w = pk2(ST[vt][1].z, ST[vt][1].w);
;                 s1w.x = pk2(ST[vt][2].x, ST[vt][2].y); s1w.y = pk2(ST[vt][2].z, ST[vt][2].w); s1w.z = pk2(ST[vt][3].x, ST[vt][3].y); s1w.w = pk2(ST[vt][3].z, ST[vt][3].w);
;                 const bf16x8 sf0 = __builtin_bit_cast(bf16x8, s0w), sf1 = __builtin_bit_cast(bf16x8, s1w);
;                 f32x4 z = __builtin_amdgcn_mfma_f32_16x16x32_bf16(az0, sf0, zero4, 0, 0, 0); z = __builtin_amdgcn_mfma_f32_16x16x32_bf16(az1, sf1, z, 0, 0, 0);
;                 const u32x2 vq = *(const LAS u32x2*)(slot + WY_VT + v * 32 + g * 8);
;                 u32x4 f1w; f1w.x = pk2(z.x, z.y); f1w.y = pk2(z.z, z.w); f1w.z = vq.x; f1w.w = vq.y;
;                 const f32x4 u = __builtin_amdgcn_mfma_f32_16x16x32_bf16(au, __builtin_bit_cast(bf16x8, f1w), zero4, 0, 0, 0);
;                 u32x4 f2w; f2w.x = pk2(u.x, u.y); f2w.y = pk2(u.z, u.w); f2w.z = vq.x; f2w.w = vq.y; const bf16x8 f2 = __builtin_bit_cast(bf16x8, f2w);
.LBB0_1413:
	s_mulk_i32 s1, 0x4500
	s_add_i32 s1, s1, 0
	v_add_u32_e32 v32, s1, v131
	v_add_u32_e32 v84, s1, v133
	v_add_u32_e32 v110, s1, v135
	v_add_u32_e32 v78, v110, v104
	v_add_u32_e32 v194, v110, v105
	ds_read_b128 v[88:91], v84
	ds_read_b128 v[106:109], v84 offset:1024
	ds_read_b128 v[56:59], v84 offset:2048
	ds_read_b128 v[52:55], v84 offset:3072
	ds_read_b128 v[68:71], v84 offset:4096
	ds_read_b64 v[82:83], v78 offset:10240
	ds_read_b64 v[188:189], v194 offset:10240
	ds_read_b128 v[44:47], v32 offset:12288
	ds_read_b128 v[40:43], v32 offset:12352
	ds_read_b128 v[36:39], v32 offset:12416
	ds_read_b128 v[32:35], v32 offset:12480
	ds_read_b128 v[166:169], v84 offset:6144
	ds_read_b128 v[170:173], v84 offset:7168
	ds_read_b128 v[174:177], v84 offset:8192
	ds_read_b128 v[178:181], v84 offset:9216
	v_cvt_pk_bf16_f32 v60, v0, v1
	v_cvt_pk_bf16_f32 v61, v2, v3
	v_cvt_pk_bf16_f32 v62, v4, v5
	v_cvt_pk_bf16_f32 v63, v6, v7
	v_cvt_pk_bf16_f32 v64, v8, v9
	v_cvt_pk_bf16_f32 v65, v10, v11
	v_cvt_pk_bf16_f32 v66, v12, v13
	v_cvt_pk_bf16_f32 v67, v14, v15
	v_cvt_pk_bf16_f32 v76, v24, v25
	v_cvt_pk_bf16_f32 v77, v26, v27
	v_cvt_pk_bf16_f32 v78, v28, v29
	v_cvt_pk_bf16_f32 v79, v30, v31
	s_lshl_b32 s84, s0, 4
	v_lshl_add_u64 v[100:101], v[92:93], 0, s[84:85]
	v_lshlrev_b64 v[98:99], 11, v[100:101]
	v_lshl_add_u64 v[100:101], v[94:95], 0, v[98:99]
	v_or_b32_e32 v98, 0x1000, v98
	v_lshl_add_u64 v[102:103], v[94:95], 0, v[98:99]
	s_waitcnt lgkmcnt(14)
	v_mfma_f32_16x16x32_bf16 v[72:75], v[88:91], v[60:63], 0
	ds_read_b128 v[48:51], v84 offset:5120
	v_cvt_pk_bf16_f32 v84, v16, v17
	v_cvt_pk_bf16_f32 v85, v18, v19
	v_cvt_pk_bf16_f32 v86, v20, v21
	v_cvt_pk_bf16_f32 v87, v22, v23
	s_waitcnt lgkmcnt(14)
	v_mfma_f32_16x16x32_bf16 v[72:75], v[106:109], v[64:67], v[72:75]
	v_mfma_f32_16x16x32_bf16 v[182:185], v[88:91], v[84:87], 0
	v_mfma_f32_16x16x32_bf16 v[182:185], v[106:109], v[76:79], v[182:185]
	s_waitcnt lgkmcnt(13)
	v_mfma_f32_16x16x32_bf16 v[190:193], v[56:59], v[60:63], 0
	v_mfma_f32_16x16x32_bf16 v[234:237], v[56:59], v[84:87], 0
	s_waitcnt lgkmcnt(12)
	v_mfma_f32_16x16x32_bf16 v[190:193], v[52:55], v[64:67], v[190:193]
	v_mfma_f32_16x16x32_bf16 v[234:237], v[52:55], v[76:79], v[234:237]
	s_nop 1
	v_cvt_pk_bf16_f32 v80, v72, v73
	v_cvt_pk_bf16_f32 v81, v74, v75
	s_nop 1
	v_cvt_pk_bf16_f32 v186, v182, v183
	v_cvt_pk_bf16_f32 v187, v184, v185
	s_waitcnt lgkmcnt(9)
	s_nop 0
	v_mfma_f32_16x16x32_bf16 v[72:75], v[68:71], v[80:83], 0
	v_mfma_f32_16x16x32_bf16 v[182:185], v[68:71], v[186:189], 0
	s_waitcnt lgkmcnt(5)
	v_pk_mul_f32 v[0:1], v[0:1], v[44:45]
	v_pk_mul_f32 v[2:3], v[2:3], v[46:47]
	v_pk_mul_f32 v[4:5], v[4:5], v[40:41]
	v_pk_mul_f32 v[6:7], v[6:7], v[42:43]
	v_pk_mul_f32 v[8:9], v[8:9], v[36:37]
	v_pk_mul_f32 v[10:11], v[10:11], v[38:39]
	v_pk_mul_f32 v[12:13], v[12:13], v[32:33]
	v_pk_mul_f32 v[14:15], v[14:15], v[34:35]
	v_cvt_pk_bf16_f32 v80, v72, v73
	v_cvt_pk_bf16_f32 v81, v74, v75
	v_pk_mul_f32 v[16:17], v[16:17], v[44:45]
	v_pk_mul_f32 v[18:19], v[18:19], v[46:47]
	v_pk_mul_f32 v[20:21], v[20:21], v[40:41]
	v_pk_mul_f32 v[22:23], v[22:23], v[42:43]
	s_waitcnt lgkmcnt(1)
	v_mfma_f32_16x16x32_bf16 v[0:3], v[166:169], v[80:83], v[0:3]
	v_mfma_f32_16x16x32_bf16 v[4:7], v[170:173], v[80:83], v[4:7]
	v_cvt_pk_bf16_f32 v186, v182, v183
	v_cvt_pk_bf16_f32 v187, v184, v185
	v_mfma_f32_16x16x32_bf16 v[8:11], v[174:177], v[80:83], v[8:11]
	v_mfma_f32_16x16x32_bf16 v[12:15], v[178:181], v[80:83], v[12:15]
	v_pk_mul_f32 v[24:25], v[24:25], v[36:37]
	v_pk_mul_f32 v[26:27], v[26:27], v[38:39]
	v_pk_mul_f32 v[28:29], v[28:29], v[32:33]
	v_pk_mul_f32 v[30:31], v[30:31], v[34:35]
	s_mul_i32 s1, s3, 0xaaab
	s_lshr_b32 s1, s1, 18
	s_mul_i32 s1, s1, 6
	s_sub_i32 s1, s3, s1
	s_and_b32 s1, s1, 0xffff
	s_lshl_b32 s1, s1, 2
	s_add_i32 s1, s1, 0x19e00
	v_mov_b32_e32 v195, s1
	v_mfma_f32_16x16x32_bf16 v[16:19], v[166:169], v[186:189], v[16:19]
	v_mfma_f32_16x16x32_bf16 v[20:23], v[170:173], v[186:189], v[20:23]
	v_mfma_f32_16x16x32_bf16 v[24:27], v[174:177], v[186:189], v[24:27]
	v_mfma_f32_16x16x32_bf16 v[28:31], v[178:181], v[186:189], v[28:31]
	ds_read_b32 v195, v195
	s_waitcnt lgkmcnt(1)
	v_mfma_f32_16x16x32_bf16 v[190:193], v[48:51], v[80:83], v[190:193]
	v_mfma_f32_16x16x32_bf16 v[234:237], v[48:51], v[186:189], v[234:237]
	s_nop 7
	global_store_dword v[100:101], v190, off
	global_store_dword v[100:101], v191, off offset:2048
	global_store_dword v[102:103], v192, off
	global_store_dword v[102:103], v193, off offset:2048
	global_store_dword v[100:101], v234, off offset:64
	global_store_dword v[100:101], v235, off offset:2112
	global_store_dword v[102:103], v236, off offset:64
	global_store_dword v[102:103], v237, off offset:2112
	s_waitcnt lgkmcnt(0)
	s_and_saveexec_b64 s[0:1], s[66:67]
	s_cbranch_execz .LBB0_1410
	v_mov_b32_e32 v32, s2
	v_mov_b32_e32 v33, s3
	ds_write_b32 v32, v33
	s_branch .LBB0_1410

; __device__ __forceinline__ float bf2f(unsigned h) { return __uint_as_float(h << 16); }
; __device__ __forceinline__ void wy_issue(const Args& a, LAS unsigned char* stg, int b, int h, int c, int lane, float (&dec)[WY_T], float (&al)[WY_T], float (&rn)[WY_T]) {
;     ...
;     for (int t = 0; t < WY_T; ++t) { dec[t] = DEC[(tok0 + t) * 512 + ch]; al[t] = bf2f(AL[(tok0 + t) * 512 + ch]); rn[t] = CT[(tok0 + t) * 8 + h]; }
; __device__ __forceinline__ void rw_wy(const Args& a, LAS unsigned char* lds, int bh, int tid) {
;     ...
;         for (int c = c_first; c < WY_NCH; c += WY_NP) {
;             while (min(__hip_atomic_load(flags + 8, __ATOMIC_ACQUIRE, __HIP_MEMORY_SCOPE_WORKGROUP), __hip_atomic_load(flags + 9, __ATOMIC_ACQUIRE, __HIP_MEMORY_SCOPE_WORKGROUP)) < c - (WY_NP - 1)) __builtin_amdgcn_s_sleep(2);
;             asm volatile("s_waitcnt vmcnt(0)" ::: "memory"); __builtin_amdgcn_wave_barrier();
;             wy_build1(a, slot, stg, h, c, lane, dec, alr, rn);
.LBB0_1421:
	s_or_b64 exec, exec, s[0:1]
	s_and_b64 vcc, exec, s[94:95]
	s_mov_b32 s90, s84
	s_cbranch_vccnz .LBB0_1381
	s_waitcnt vmcnt(0)
	v_lshlrev_b32_e32 v26, 16, v26
	v_lshlrev_b32_e32 v27, 16, v27
	v_lshlrev_b32_e32 v28, 16, v28
	v_lshlrev_b32_e32 v29, 16, v29
	v_lshlrev_b32_e32 v30, 16, v30
	v_lshlrev_b32_e32 v31, 16, v31
	v_lshlrev_b32_e32 v32, 16, v32
	v_lshlrev_b32_e32 v33, 16, v33
	v_lshlrev_b32_e32 v34, 16, v34
	v_lshlrev_b32_e32 v35, 16, v35
	v_lshlrev_b32_e32 v58, 16, v58
	v_lshlrev_b32_e32 v59, 16, v59
	v_lshlrev_b32_e32 v64, 16, v64
	v_lshlrev_b32_e32 v65, 16, v65
	v_lshlrev_b32_e32 v76, 16, v76
	v_lshlrev_b32_e32 v77, 16, v77

; #define LAS __attribute__((address_space(3)))
; __device__ __forceinline__ float bf2f(unsigned h) { return __uint_as_float(h << 16); }
; __device__ __forceinline__ void wy_issue(const Args& a, LAS unsigned char* stg, int b, int h, int c, int lane, float (&dec)[WY_T], float (&al)[WY_T], float (&rn)[WY_T]) {
;     unsigned char* ws = a.ws;
;     const bf16* PR = (const bf16*)(ws + WS_PRW); const float* DEC = (const float*)(ws + WS_DEC); const bf16* AL = (const bf16*)(ws + WS_AL); const float* CT = (const float*)(ws + WS_CT);
;     const size_t tok0 = (size_t)b * SEQ + (size_t)c * WY_T; const int ch = h * 64 + lane;
; #pragma unroll
;     for (int j = 0; j < 7; ++j) { const int idx = j * 64 + lane;
;         if (idx < 408) { const int row = idx >> 3, trel = row / 3, vec = row - 3 * trel; size_t tk = tok0 + trel; tk = (tk == 0) ? 1 : tk;
;             __builtin_amdgcn_global_load_lds((const unsigned*)(PR + (tk - 1) * 1792 + vec * 512 + h * 64 + (idx & 7) * 8), (LAS unsigned*)(stg + j * 1024), 16, 0, 0); } }
; #pragma unroll
;     for (int t = 0; t < WY_T; ++t) { dec[t] = DEC[(tok0 + t) * 512 + ch]; al[t] = bf2f(AL[(tok0 + t) * 512 + ch]); rn[t] = CT[(tok0 + t) * 8 + h]; }
; }
.LBB0_1427:
	s_or_b64 exec, exec, s[0:1]
	s_lshl_b64 s[0:1], s[96:97], 9
	v_mov_b32_e32 v3, s1
	v_or_b32_e32 v2, s0, v24
	s_lshl_b64 s[0:1], s[96:97], 5
	s_add_u32 s0, s91, s0
	v_lshl_add_u64 v[0:1], v[2:3], 2, s[50:51]
	s_addc_u32 s1, s68, s1
	global_load_dword v0, v[0:1], off
	v_lshl_add_u64 v[2:3], v[2:3], 1, s[60:61]
	global_load_dword v60, v119, s[0:1]
	s_or_b32 s0, s96, 1
	s_mov_b32 s1, s97
	s_lshl_b64 s[30:31], s[0:1], 9
	v_mov_b32_e32 v5, s31
	v_or_b32_e32 v4, s30, v24
	v_lshl_add_u64 v[6:7], v[4:5], 2, s[50:51]
	v_lshl_add_u64 v[4:5], v[4:5], 1, s[60:61]
	global_load_dword v1, v[6:7], off
	s_nop 0
	global_load_ushort v27, v[4:5], off
	s_nop 0
	global_load_ushort v26, v[2:3], off
	s_lshl_b64 s[0:1], s[0:1], 5
	s_add_u32 s0, s91, s0
	s_addc_u32 s1, s68, s1
	global_load_dword v61, v119, s[0:1]
	s_or_b32 s0, s96, 2
	s_mov_b32 s1, s97
	s_lshl_b64 s[30:31], s[0:1], 9
	s_lshl_b64 s[0:1], s[0:1], 5
	v_mov_b32_e32 v5, s31
	s_add_u32 s0, s91, s0
	s_addc_u32 s1, s68, s1
	global_load_dword v62, v119, s[0:1]
	s_or_b32 s0, s96, 3
	s_mov_b32 s1, s97
	v_or_b32_e32 v4, s30, v24
	v_lshl_add_u64 v[2:3], v[4:5], 2, s[50:51]
	global_load_dword v2, v[2:3], off
	s_lshl_b64 s[30:31], s[0:1], 9
	v_mov_b32_e32 v7, s31
	v_or_b32_e32 v6, s30, v24
	v_lshl_add_u64 v[4:5], v[4:5], 1, s[60:61]
	v_lshl_add_u64 v[8:9], v[6:7], 2, s[50:51]
	v_lshl_add_u64 v[6:7], v[6:7], 1, s[60:61]
	global_load_dword v3, v[8:9], off
	s_nop 0
	global_load_ushort v29, v[6:7], off
	s_nop 0
	global_load_ushort v28, v[4:5], off
	s_lshl_b64 s[0:1], s[0:1], 5
	s_add_u32 s0, s91, s0
	s_addc_u32 s1, s68, s1
	global_load_dword v63, v119, s[0:1]
	s_or_b32 s0, s96, 4
	s_mov_b32 s1, s97
	s_lshl_b64 s[30:31], s[0:1], 9
	s_lshl_b64 s[0:1], s[0:1], 5
	v_mov_b32_e32 v7, s31
	s_add_u32 s0, s91, s0
	s_addc_u32 s1, s68, s1
	global_load_dword v66, v119, s[0:1]
	s_or_b32 s0, s96, 5
	s_mov_b32 s1, s97
	v_or_b32_e32 v6, s30, v24
	v_lshl_add_u64 v[4:5], v[6:7], 2, s[50:51]
	global_load_dword v4, v[4:5], off
	s_lshl_b64 s[30:31], s[0:1], 9
	v_mov_b32_e32 v9, s31
	v_or_b32_e32 v8, s30, v24
	v_lshl_add_u64 v[6:7], v[6:7], 1, s[60:61]
	v_lshl_add_u64 v[10:11], v[8:9], 2, s[50:51]
	v_lshl_add_u64 v[8:9], v[8:9], 1, s[60:61]
	global_load_dword v5, v[10:11], off
	s_nop 0
	global_load_ushort v31, v[8:9], off
	s_nop 0
	global_load_ushort v30, v[6:7], off
	s_lshl_b64 s[0:1], s[0:1], 5
	s_add_u32 s0, s91, s0
	s_addc_u32 s1, s68, s1
	global_load_dword v67, v119, s[0:1]
	s_or_b32 s0, s96, 6
	s_mov_b32 s1, s97
	s_lshl_b64 s[30:31], s[0:1], 9
	s_lshl_b64 s[0:1], s[0:1], 5
	v_mov_b32_e32 v9, s31
	s_add_u32 s0, s91, s0
	s_addc_u32 s1, s68, s1
	global_load_dword v68, v119, s[0:1]
	s_or_b32 s0, s96, 7
	s_mov_b32 s1, s97
	v_or_b32_e32 v8, s30, v24
	v_lshl_add_u64 v[6:7], v[8:9], 2, s[50:51]
	global_load_dword v6, v[6:7], off
	s_lshl_b64 s[30:31], s[0:1], 9
	v_mov_b32_e32 v11, s31
	v_or_b32_e32 v10, s30, v24
	v_lshl_add_u64 v[8:9], v[8:9], 1, s[60:61]
	v_lshl_add_u64 v[12:13], v[10:11], 2, s[50:51]
	v_lshl_add_u64 v[10:11], v[10:11], 1, s[60:61]
	global_load_dword v7, v[12:13], off
	s_nop 0
	global_load_ushort v33, v[10:11], off
	s_nop 0
	global_load_ushort v32, v[8:9], off
	s_lshl_b64 s[0:1], s[0:1], 5
	s_add_u32 s0, s91, s0
	s_addc_u32 s1, s68, s1
	global_load_dword v69, v119, s[0:1]
	s_or_b32 s0, s96, 8
	s_mov_b32 s1, s97
	s_lshl_b64 s[30:31], s[0:1], 9
	s_lshl_b64 s[0:1], s[0:1], 5
	v_mov_b32_e32 v11, s31
	s_add_u32 s0, s91, s0
	s_addc_u32 s1, s68, s1
	global_load_dword v70, v119, s[0:1]
	s_or_b32 s0, s96, 9
	s_mov_b32 s1, s97
	v_or_b32_e32 v10, s30, v24
	v_lshl_add_u64 v[8:9], v[10:11], 2, s[50:51]
	global_load_dword v8, v[8:9], off
	s_lshl_b64 s[30:31], s[0:1], 9
	v_mov_b32_e32 v13, s31
	v_or_b32_e32 v12, s30, v24
	v_lshl_add_u64 v[10:11], v[10:11], 1, s[60:61]
	v_lshl_add_u64 v[14:15], v[12:13], 2, s[50:51]
	v_lshl_add_u64 v[12:13], v[12:13], 1, s[60:61]
	global_load_dword v9, v[14:15], off
	s_nop 0
	global_load_ushort v35, v[12:13], off
	s_nop 0
	global_load_ushort v34, v[10:11], off
	s_lshl_b64 s[0:1], s[0:1], 5
	s_add_u32 s0, s91, s0
	s_addc_u32 s1, s68, s1
	global_load_dword v71, v119, s[0:1]
	s_or_b32 s0, s96, 10
	s_mov_b32 s1, s97
	s_lshl_b64 s[30:31], s[0:1], 9
	s_lshl_b64 s[0:1], s[0:1], 5
	v_mov_b32_e32 v13, s31
	s_add_u32 s0, s91, s0
	s_addc_u32 s1, s68, s1
	global_load_dword v72, v119, s[0:1]
	s_or_b32 s0, s96, 11
	s_mov_b32 s1, s97
	v_or_b32_e32 v12, s30, v24
	v_lshl_add_u64 v[10:11], v[12:13], 2, s[50:51]
	global_load_dword v10, v[10:11], off
	s_lshl_b64 s[30:31], s[0:1], 9
	v_mov_b32_e32 v15, s31
	v_or_b32_e32 v14, s30, v24
	v_lshl_add_u64 v[12:13], v[12:13], 1, s[60:61]
	v_lshl_add_u64 v[16:17], v[14:15], 2, s[50:51]
	v_lshl_add_u64 v[14:15], v[14:15], 1, s[60:61]
	global_load_dword v11, v[16:17], off
	s_nop 0
	global_load_ushort v59, v[14:15], off
	s_nop 0
	global_load_ushort v58, v[12:13], off
	s_lshl_b64 s[0:1], s[0:1], 5
	s_add_u32 s0, s91, s0
	s_addc_u32 s1, s68, s1
	global_load_dword v73, v119, s[0:1]
	s_or_b32 s0, s96, 12
	s_mov_b32 s1, s97
	s_lshl_b64 s[30:31], s[0:1], 9
	s_lshl_b64 s[0:1], s[0:1], 5
	v_mov_b32_e32 v15, s31
	s_add_u32 s0, s91, s0
	s_addc_u32 s1, s68, s1
	global_load_dword v74, v119, s[0:1]
	s_or_b32 s0, s96, 13
	s_mov_b32 s1, s97
	v_or_b32_e32 v14, s30, v24
	v_lshl_add_u64 v[12:13], v[14:15], 2, s[50:51]
	global_load_dword v12, v[12:13], off
	s_lshl_b64 s[30:31], s[0:1], 9
	v_mov_b32_e32 v17, s31
	v_or_b32_e32 v16, s30, v24
	v_lshl_add_u64 v[14:15], v[14:15], 1, s[60:61]
	v_lshl_add_u64 v[18:19], v[16:17], 2, s[50:51]
	v_lshl_add_u64 v[16:17], v[16:17], 1, s[60:61]
	global_load_dword v13, v[18:19], off
	s_nop 0
	global_load_ushort v65, v[16:17], off
	s_nop 0
	global_load_ushort v64, v[14:15], off
	s_lshl_b64 s[0:1], s[0:1], 5
	s_add_u32 s0, s91, s0
	s_addc_u32 s1, s68, s1
	global_load_dword v75, v119, s[0:1]
	s_or_b32 s0, s96, 14
	s_mov_b32 s1, s97
	s_lshl_b64 s[30:31], s[0:1], 9
	s_lshl_b64 s[0:1], s[0:1], 5
	v_mov_b32_e32 v17, s31
	s_add_u32 s0, s91, s0
	s_addc_u32 s1, s68, s1
	s_or_b32 s96, s96, 15
	global_load_dword v36, v119, s[0:1]
	s_lshl_b64 s[0:1], s[96:97], 9
	v_mov_b32_e32 v19, s1
	v_or_b32_e32 v18, s0, v24
	s_lshl_b64 s[0:1], s[96:97], 5
	v_lshl_add_u64 v[22:23], v[18:19], 2, s[50:51]
	v_lshl_add_u64 v[18:19], v[18:19], 1, s[60:61]
	s_add_u32 s0, s91, s0
	s_addc_u32 s1, s68, s1
	v_or_b32_e32 v16, s30, v24
	v_lshl_add_u64 v[14:15], v[16:17], 2, s[50:51]
	global_load_dword v14, v[14:15], off
	v_lshl_add_u64 v[16:17], v[16:17], 1, s[60:61]
	global_load_dword v15, v[22:23], off
	s_nop 0
	global_load_ushort v77, v[18:19], off
	s_nop 0
	global_load_ushort v76, v[16:17], off
	global_load_dword v37, v119, s[0:1]

; #define LAS __attribute__((address_space(3)))
; __device__ __forceinline__ void attn_unit(const bf16* QB, const bf16* KN, const bf16* KR, const bf16* VT, bf16* YC, LAS unsigned char* lds, int b, int h, int u, int tid, int lane, int wave) {
;     ...
;     for (int kt = 0; kt < nt_unit; ++kt) {
;         if (kt + 1 < nt_unit) { LAS unsigned char* nx = lds + ((kt + 1) & 1) * AT_STAGE;
; #pragma unroll
;             for (int i = 0; i < 2; ++i) { *(LAS u32x4*)(nx + kndst[i]) = kreg[i]; *(LAS u32x4*)(nx + vtdst[i]) = vreg[i]; }
;             *(LAS u32x4*)(nx + krdst) = kreg[2];
;             if (kt + 2 < nt_unit) { const unsigned t2 = (unsigned)(kt + 2) * 64u;
; #pragma unroll
;                 for (int i = 0; i < 2; ++i) { kreg[i] = *(const u32x4*)(KN + (knoff[i] + t2 * 512u)); vreg[i] = *(const u32x4*)(VT + (vtoff[i] + t2)); }
;                 kreg[2] = *(const u32x4*)(KR + (kroff + t2 * 64u)); }
;         }
;         LAS unsigned char* st = lds + (kt & 1) * AT_STAGE;
;         if (kt < nt_wave) {
;             f32x16 sa[2];
; #pragma unroll
;             for (int mt = 0; mt < 2; ++mt) {
; #pragma unroll
;                 for (int i = 0; i < 16; ++i) sa[mt][i] = 0.f;
; #pragma unroll
;                 for (int ks = 0; ks < 12; ++ks) { const bf16x8 af = *(const LAS bf16x8*)(st + (32 * mt + r32) * AT_KSTR + 32 * ks + 16 * hi);
;                     sa[mt] = __builtin_amdgcn_mfma_f32_32x32x16_bf16(af, qf[ks], sa[mt], 0, 0, 0); }
;             }
;             float mx = sa[0][0];
; #pragma unroll
;             for (int i = 1; i < 16; ++i) mx = fmaxf(mx, sa[0][i]);
; #pragma unroll
;             for (int i = 0; i < 16; ++i) mx = fmaxf(mx, sa[1][i]);
;             mx = fmaxf(mx, __shfl_xor(mx, 32));
;             const bool grow = __builtin_amdgcn_ballot_w64(mx - m_run > 8.0f) != 0ull;
;             const float m_new = grow ? fmaxf(m_run, mx) : m_run; const float alpha = grow ? __builtin_amdgcn_exp2f(m_run - m_new) : 1.0f; m_run = m_new;
.LBB0_1470:
	s_add_i32 s6, s4, 1
	s_bitcmp1_b32 s6, 0
	s_cselect_b32 s5, 0xac00, 0
	s_add_i32 s28, s5, 0
	v_add_u32_e32 v64, s28, v170
	s_waitcnt vmcnt(4)
	ds_write_b128 v64, v[148:151]
	v_add_u32_e32 v64, s28, v174
	s_waitcnt vmcnt(3)
	ds_write_b128 v64, v[144:147] offset:25600
	v_add_u32_e32 v64, s28, v172
	s_waitcnt vmcnt(2)
	ds_write_b128 v64, v[156:159]
	v_add_u32_e32 v64, s28, v176
	s_waitcnt vmcnt(1)
	ds_write_b128 v64, v[152:155] offset:25600
	v_add_u32_e32 v64, s28, v192
	v_add_u32_e32 v66, v188, v207
	v_mov_b32_e32 v67, v169
	s_waitcnt vmcnt(0)
	ds_write_b128 v64, v[160:163] offset:256
	v_lshl_add_u64 v[64:65], v[168:169], 1, s[62:63]
	v_lshl_add_u64 v[66:67], v[66:67], 1, s[48:49]
	v_mov_b32_e32 v185, v169
	global_load_dwordx4 v[148:151], v[64:65], off
	global_load_dwordx4 v[144:147], v[66:67], off
	v_lshl_add_u64 v[64:65], v[184:185], 1, s[62:63]
	v_add_u32_e32 v66, v188, v206
	v_mov_b32_e32 v67, v169
	v_lshl_add_u64 v[66:67], v[66:67], 1, s[48:49]
	global_load_dwordx4 v[156:159], v[64:65], off
	global_load_dwordx4 v[152:155], v[66:67], off
	v_add_u32_e32 v64, v188, v181
	v_mov_b32_e32 v65, v169
	v_lshl_add_u64 v[64:65], v[64:65], 1, s[54:55]
	global_load_dwordx4 v[160:163], v[64:65], off
	s_cmp_gt_i32 s4, s0
	s_cbranch_scc1 .LBB0_1474
	s_bitcmp1_b32 s4, 0
	s_cselect_b32 s4, 0xac00, 0
	v_add_u32_e32 v208, s4, v199
	v_add_u32_e32 v72, v208, v194
	v_add_u32_e32 v185, v208, v195
	ds_read_b128 v[210:213], v72
	ds_read_b128 v[214:217], v72 offset:32
	ds_read_b128 v[218:221], v72 offset:64
	ds_read_b128 v[222:225], v72 offset:96
	s_waitcnt lgkmcnt(3)
	v_mfma_f32_32x32x16_bf16 v[80:95], v[210:213], v[140:143], 0
	ds_read_b128 v[226:229], v72 offset:128
	s_waitcnt lgkmcnt(3)
	v_mfma_f32_32x32x16_bf16 v[80:95], v[214:217], v[136:139], v[80:95]
	ds_read_b128 v[210:213], v72 offset:160
	s_waitcnt lgkmcnt(3)
	v_mfma_f32_32x32x16_bf16 v[80:95], v[218:221], v[132:135], v[80:95]
	ds_read_b128 v[214:217], v72 offset:192
	s_waitcnt lgkmcnt(3)
	v_mfma_f32_32x32x16_bf16 v[80:95], v[222:225], v[128:131], v[80:95]
	ds_read_b128 v[218:221], v72 offset:224
	s_waitcnt lgkmcnt(3)
	v_mfma_f32_32x32x16_bf16 v[80:95], v[226:229], v[124:127], v[80:95]
	ds_read_b128 v[222:225], v72 offset:256
	s_waitcnt lgkmcnt(3)
	v_mfma_f32_32x32x16_bf16 v[80:95], v[210:213], v[120:123], v[80:95]
	ds_read_b128 v[226:229], v72 offset:288
	s_waitcnt lgkmcnt(3)
	v_mfma_f32_32x32x16_bf16 v[80:95], v[214:217], v[116:119], v[80:95]
	ds_read_b128 v[210:213], v72 offset:320
	s_waitcnt lgkmcnt(3)
	v_mfma_f32_32x32x16_bf16 v[80:95], v[218:221], v[112:115], v[80:95]
	ds_read_b128 v[214:217], v72 offset:352
	s_waitcnt lgkmcnt(3)
	v_mfma_f32_32x32x16_bf16 v[80:95], v[222:225], v[108:111], v[80:95]
	ds_read_b128 v[218:221], v185
	s_waitcnt lgkmcnt(3)
	v_mfma_f32_32x32x16_bf16 v[80:95], v[226:229], v[104:107], v[80:95]
	ds_read_b128 v[222:225], v185 offset:32
	s_waitcnt lgkmcnt(3)
	v_mfma_f32_32x32x16_bf16 v[80:95], v[210:213], v[100:103], v[80:95]
	ds_read_b128 v[226:229], v185 offset:64
	s_waitcnt lgkmcnt(3)
	v_mfma_f32_32x32x16_bf16 v[80:95], v[214:217], v[96:99], v[80:95]
	ds_read_b128 v[210:213], v185 offset:96
	s_waitcnt lgkmcnt(3)
	v_mfma_f32_32x32x16_bf16 v[64:79], v[218:221], v[140:143], 0
	ds_read_b128 v[214:217], v185 offset:128
	s_waitcnt lgkmcnt(3)
	v_mfma_f32_32x32x16_bf16 v[64:79], v[222:225], v[136:139], v[64:79]
	ds_read_b128 v[218:221], v185 offset:160
	s_waitcnt lgkmcnt(3)
	v_mfma_f32_32x32x16_bf16 v[64:79], v[226:229], v[132:135], v[64:79]
	ds_read_b128 v[222:225], v185 offset:192
	s_waitcnt lgkmcnt(3)
	v_mfma_f32_32x32x16_bf16 v[64:79], v[210:213], v[128:131], v[64:79]
	ds_read_b128 v[226:229], v185 offset:224
	s_waitcnt lgkmcnt(3)
	v_mfma_f32_32x32x16_bf16 v[64:79], v[214:217], v[124:127], v[64:79]
	ds_read_b128 v[210:213], v185 offset:256
	v_max_f32_e32 v209, v80, v81
	v_max3_f32 v209, v209, v82, v83
	s_waitcnt lgkmcnt(3)
	v_mfma_f32_32x32x16_bf16 v[64:79], v[218:221], v[120:123], v[64:79]
	ds_read_b128 v[214:217], v185 offset:288
	v_max3_f32 v209, v209, v84, v85
	s_waitcnt lgkmcnt(3)
	v_mfma_f32_32x32x16_bf16 v[64:79], v[222:225], v[116:119], v[64:79]
	ds_read_b128 v[218:221], v185 offset:320
	v_max3_f32 v209, v209, v86, v87
	s_waitcnt lgkmcnt(3)
	v_mfma_f32_32x32x16_bf16 v[64:79], v[226:229], v[112:115], v[64:79]
	ds_read_b128 v[222:225], v185 offset:352
	v_max3_f32 v209, v209, v88, v89
	s_waitcnt lgkmcnt(3)
	v_mfma_f32_32x32x16_bf16 v[64:79], v[210:213], v[108:111], v[64:79]
	v_max3_f32 v209, v209, v90, v91
	v_and_b32_e32 v226, 64, v167
	s_waitcnt lgkmcnt(2)
	v_mfma_f32_32x32x16_bf16 v[64:79], v[214:217], v[104:107], v[64:79]
	v_max3_f32 v209, v209, v92, v93
	v_xor_b32_e32 v227, 32, v167
	s_waitcnt lgkmcnt(1)
	v_mfma_f32_32x32x16_bf16 v[64:79], v[218:221], v[100:103], v[64:79]
	v_max3_f32 v209, v209, v94, v95
	v_add_u32_e32 v226, 64, v226
	s_waitcnt lgkmcnt(0)
	v_mfma_f32_32x32x16_bf16 v[64:79], v[222:225], v[96:99], v[64:79]
	v_cmp_lt_i32_e32 vcc, v227, v226
	s_nop 1
	v_cndmask_b32_e32 v227, v167, v227, vcc
	v_lshlrev_b32_e32 v227, 2, v227
	s_nop 7
	v_max3_f32 v185, v209, v64, v65
	v_max3_f32 v185, v185, v66, v67
	v_max3_f32 v185, v185, v68, v69
	v_max3_f32 v185, v185, v70, v71
	v_max3_f32 v185, v185, v72, v73
	v_max3_f32 v185, v185, v74, v75
	v_max3_f32 v185, v185, v76, v77
	v_max3_f32 v185, v185, v78, v79
	ds_bpermute_b32 v209, v227, v185
	s_waitcnt lgkmcnt(0)
	v_max_f32_e32 v209, v209, v209
	v_max_f32_e32 v185, v185, v209
	v_sub_f32_e32 v209, v185, v186
	v_cmp_lt_f32_e32 vcc, s72, v209
	s_cmp_eq_u64 vcc, 0
	v_max_f32_e32 v209, v186, v186
	v_max_f32_e32 v185, v209, v185
	s_cselect_b64 s[4:5], -1, 0
	v_cndmask_b32_e64 v185, v185, v186, s[4:5]
	v_sub_f32_e32 v186, v186, v185
	v_exp_f32_e32 v186, v186
	s_and_b64 vcc, exec, s[4:5]
	s_cbranch_vccnz .LBB0_1473
; __device__ __forceinline__ void attn_unit(const bf16* QB, const bf16* KN, const bf16* KR, const bf16* VT, bf16* YC, LAS unsigned char* lds, int b, int h, int u, int tid, int lane, int wave) {
;     ...
;             if (grow) {
; #pragma unroll
;                 for (int d = 0; d < 4; ++d)
; #pragma unroll
;                     for (int i = 0; i < 16; ++i) ot[d][i] *= alpha;
;             }
	v_pk_mul_f32 v[62:63], v[62:63], v[186:187] op_sel_hi:[1,0]
	v_pk_mul_f32 v[60:61], v[60:61], v[186:187] op_sel_hi:[1,0]
	v_pk_mul_f32 v[58:59], v[58:59], v[186:187] op_sel_hi:[1,0]
	v_pk_mul_f32 v[56:57], v[56:57], v[186:187] op_sel_hi:[1,0]
	v_pk_mul_f32 v[54:55], v[54:55], v[186:187] op_sel_hi:[1,0]
	v_pk_mul_f32 v[52:53], v[52:53], v[186:187] op_sel_hi:[1,0]
	v_pk_mul_f32 v[50:51], v[50:51], v[186:187] op_sel_hi:[1,0]
	v_pk_mul_f32 v[48:49], v[48:49], v[186:187] op_sel_hi:[1,0]
	v_pk_mul_f32 v[46:47], v[46:47], v[186:187] op_sel_hi:[1,0]
	v_pk_mul_f32 v[44:45], v[44:45], v[186:187] op_sel_hi:[1,0]
	v_pk_mul_f32 v[42:43], v[42:43], v[186:187] op_sel_hi:[1,0]
	v_pk_mul_f32 v[40:41], v[40:41], v[186:187] op_sel_hi:[1,0]
	v_pk_mul_f32 v[38:39], v[38:39], v[186:187] op_sel_hi:[1,0]
	v_pk_mul_f32 v[36:37], v[36:37], v[186:187] op_sel_hi:[1,0]
	v_pk_mul_f32 v[34:35], v[34:35], v[186:187] op_sel_hi:[1,0]
	v_pk_mul_f32 v[32:33], v[32:33], v[186:187] op_sel_hi:[1,0]
	v_pk_mul_f32 v[30:31], v[30:31], v[186:187] op_sel_hi:[1,0]
	v_pk_mul_f32 v[28:29], v[28:29], v[186:187] op_sel_hi:[1,0]
	v_pk_mul_f32 v[26:27], v[26:27], v[186:187] op_sel_hi:[1,0]
	v_pk_mul_f32 v[24:25], v[24:25], v[186:187] op_sel_hi:[1,0]
	v_pk_mul_f32 v[22:23], v[22:23], v[186:187] op_sel_hi:[1,0]
	v_pk_mul_f32 v[20:21], v[20:21], v[186:187] op_sel_hi:[1,0]
	v_pk_mul_f32 v[18:19], v[18:19], v[186:187] op_sel_hi:[1,0]
	v_pk_mul_f32 v[16:17], v[16:17], v[186:187] op_sel_hi:[1,0]
	v_pk_mul_f32 v[14:15], v[14:15], v[186:187] op_sel_hi:[1,0]
	v_pk_mul_f32 v[12:13], v[12:13], v[186:187] op_sel_hi:[1,0]
	v_pk_mul_f32 v[10:11], v[10:11], v[186:187] op_sel_hi:[1,0]
	v_pk_mul_f32 v[8:9], v[8:9], v[186:187] op_sel_hi:[1,0]
	v_pk_mul_f32 v[6:7], v[6:7], v[186:187] op_sel_hi:[1,0]
	v_pk_mul_f32 v[4:5], v[4:5], v[186:187] op_sel_hi:[1,0]
	v_pk_mul_f32 v[2:3], v[2:3], v[186:187] op_sel_hi:[1,0]
	v_pk_mul_f32 v[0:1], v[0:1], v[186:187] op_sel_hi:[1,0]
